# static priority raise: s_setprio 1 for waves 4-7 (younger half) inside the GEMM k-loops (UP, INPROJ, DOWN), reset at loop exit
# speedup vs baseline: 1.0049x; 1.0030x over previous
; #define MFMA(a, b, c) __builtin_amdgcn_mfma_f32_32x32x16_bf16((a), (b), (c), 0, 0, 0)
;     ...
;     auto issue_at = [&](int mm0, int nn0, int kt, int buf) {
;       char* lb = L0 + buf * BUFB;
; #pragma unroll
;       for (int i = 0; i < 4; ++i) {
;         const int seg = wv * 4 + i, row = seg * 8 + gl_row;
;         const int c = (lane & 7) ^ ((row >> 1) & 7);
;         const u16* ap = (kt < g.split) ? g.a0 + (size_t)(mm0 + row) * g.ld0 + kt * g.ks0 : g.a1 + (size_t)(mm0 + row) * g.ld1 + (kt - g.split) * 64;
;         __builtin_amdgcn_global_load_lds((const unsigned*)(ap + c * 8), (__attribute__((address_space(3))) unsigned*)(lb + seg * 1024 + lane * 16), 16, 0, 0);
;       }
; #pragma unroll
;       for (int i = 0; i < BN / 64; ++i) {
;         const int seg = wv * (BN / 64) + i, row = seg * 8 + gl_row;
;         const int c = (lane & 7) ^ ((row >> 1) & 7);
;         __builtin_amdgcn_global_load_lds((const unsigned*)(g.W + (size_t)(nn0 + row) * g.K + kt * 64 + c * 8),
;                                          (__attribute__((address_space(3))) unsigned*)(lb + 256 * 128 + seg * 1024 + lane * 16), 16, 0, 0);
;       }
;     };
;     auto issue = [&](int kt, int buf) { issue_at(m0, n0, kt, buf); };
;     auto compute2 = [&](int buf) {
;       const char* lb = L0 + buf * BUFB;
; #pragma unroll
;       for (int ks = 0; ks < 4; ++ks) {
;         const int c = ks * 2 + hh;
;         bf16x8 wf[2], xf[MI];
; #pragma unroll
;         for (int j = 0; j < 2; ++j) { const int r = wn * 64 + j * 32 + l32; wf[j] = *(const bf16x8*)(lb + 256 * 128 + r * 128 + ((c ^ ((r >> 1) & 7)) << 4)); }
; #pragma unroll
;         for (int i = 0; i < MI; ++i) { const int r = wm * (MI * 32) + i * 32 + l32; xf[i] = *(const bf16x8*)(lb + r * 128 + ((c ^ ((r >> 1) & 7)) << 4)); }
; #pragma unroll
;         for (int i = 0; i < MI; ++i) {
;           acc[i][0] = MFMA(wf[0], xf[i], acc[i][0]);
;           acc[i][1] = MFMA(wf[1], xf[i], acc[i][1]);
;         }
;       }
.LBB0_798:
	v_writelane_b32 v255, s60, 0
	v_writelane_b32 v255, s61, 1
	v_writelane_b32 v255, s62, 2
	v_writelane_b32 v255, s63, 3
	v_writelane_b32 v255, s64, 4
	v_add_u32_e32 v0, v168, v169
	v_add_u32_e32 v178, v160, v169
	v_add_u32_e32 v199, v162, v169
	v_add_u32_e32 v254, v166, v169
	s_nop 0
	v_readfirstlane_b32 s60, v0
	v_readfirstlane_b32 s61, v178
	v_readfirstlane_b32 s62, v199
	v_readfirstlane_b32 s63, v254
	v_readfirstlane_b32 s98, v179
	s_nop 3
	s_lshr_b32 s98, s98, 6
	s_cmp_ge_u32 s98, 4
	s_cbranch_scc0 .Lgemm_prio_798
	s_setprio 1
.Lgemm_prio_798:
	s_and_b32 s14, s11, 0x10000
	s_xor_b32 s15, s14, 0x10000
	s_add_i32 s15, s15, 0
	s_add_i32 s14, s14, 0
	v_add_u32_e32 v0, s14, v175
	v_add_u32_e32 v176, v0, v171
	v_add_u32_e32 v0, v0, v170
	ds_read_b128 v[200:203], v176 offset:32768
	ds_read_b128 v[204:207], v176 offset:36864
	ds_read_b128 v[208:211], v0
	ds_read_b128 v[212:215], v0 offset:4096
	ds_read_b128 v[216:219], v0 offset:8192
	ds_read_b128 v[220:223], v0 offset:12288
	s_add_i32 s64, s15, 0x8000
	s_add_i32 m0, s15, s60
	v_lshl_add_u64 v[176:177], v[152:153], 0, s[2:3]
	global_load_lds_dwordx4 v[176:177], off
	s_add_i32 m0, s15, s61
	v_lshl_add_u64 v[176:177], v[150:151], 0, s[2:3]
	global_load_lds_dwordx4 v[176:177], off
	s_add_i32 m0, s15, s62
	v_lshl_add_u64 v[176:177], v[148:149], 0, s[2:3]
	global_load_lds_dwordx4 v[176:177], off
	s_add_i32 m0, s15, s63
	v_lshl_add_u64 v[176:177], v[146:147], 0, s[2:3]
	global_load_lds_dwordx4 v[176:177], off
	s_add_i32 m0, s64, s60
	v_lshl_add_u64 v[176:177], v[144:145], 0, s[2:3]
	global_load_lds_dwordx4 v[176:177], off
	s_add_i32 m0, s64, s61
	v_lshl_add_u64 v[176:177], v[142:143], 0, s[2:3]
	global_load_lds_dwordx4 v[176:177], off
	s_add_i32 m0, s64, s62
	v_lshl_add_u64 v[176:177], v[140:141], 0, s[2:3]
	global_load_lds_dwordx4 v[176:177], off
	s_add_i32 m0, s64, s63
	v_lshl_add_u64 v[176:177], v[138:139], 0, s[2:3]
	global_load_lds_dwordx4 v[176:177], off
	v_add_u32_e32 v0, s14, v174
	v_add_u32_e32 v176, v0, v171
	v_add_u32_e32 v0, v0, v170
	s_waitcnt lgkmcnt(3)
	v_mfma_f32_32x32x16_bf16 v[114:129], v[200:203], v[208:211], 0
	s_add_i32 s11, s11, 0x10000
	s_add_u32 s2, s2, 0x80
	s_addc_u32 s3, s3, 0
	s_cmpk_eq_i32 s2, 0x780
	ds_read_b128 v[224:227], v176 offset:32768
	v_mfma_f32_32x32x16_bf16 v[98:113], v[204:207], v[208:211], 0
	ds_read_b128 v[228:231], v176 offset:36864
	s_waitcnt lgkmcnt(4)
	v_mfma_f32_32x32x16_bf16 v[82:97], v[200:203], v[212:215], 0
	ds_read_b128 v[232:235], v0
	v_mfma_f32_32x32x16_bf16 v[66:81], v[204:207], v[212:215], 0
	ds_read_b128 v[240:243], v0 offset:4096
	s_waitcnt lgkmcnt(5)
	v_mfma_f32_32x32x16_bf16 v[50:65], v[200:203], v[216:219], 0
	ds_read_b128 v[244:247], v0 offset:8192
	v_mfma_f32_32x32x16_bf16 v[34:49], v[204:207], v[216:219], 0
	ds_read_b128 v[248:251], v0 offset:12288
	s_waitcnt lgkmcnt(6)
	v_mfma_f32_32x32x16_bf16 v[18:33], v[200:203], v[220:223], 0
	v_mfma_f32_32x32x16_bf16 v[2:17], v[204:207], v[220:223], 0
	s_branch .Lgemm_g1_798

;     ...
;     auto issue_at = [&](int mm0, int nn0, int kt, int buf) {
;       char* lb = L0 + buf * BUFB;
; #pragma unroll
;       for (int i = 0; i < 4; ++i) {
;         const int seg = wv * 4 + i, row = seg * 8 + gl_row;
;         const int c = (lane & 7) ^ ((row >> 1) & 7);
;         const u16* ap = (kt < g.split) ? g.a0 + (size_t)(mm0 + row) * g.ld0 + kt * g.ks0 : g.a1 + (size_t)(mm0 + row) * g.ld1 + (kt - g.split) * 64;
;         __builtin_amdgcn_global_load_lds((const unsigned*)(ap + c * 8), (__attribute__((address_space(3))) unsigned*)(lb + seg * 1024 + lane * 16), 16, 0, 0);
;       }
; #pragma unroll
;       for (int i = 0; i < BN / 64; ++i) {
;         const int seg = wv * (BN / 64) + i, row = seg * 8 + gl_row;
;         const int c = (lane & 7) ^ ((row >> 1) & 7);
;         __builtin_amdgcn_global_load_lds((const unsigned*)(g.W + (size_t)(nn0 + row) * g.K + kt * 64 + c * 8),
;                                          (__attribute__((address_space(3))) unsigned*)(lb + 256 * 128 + seg * 1024 + lane * 16), 16, 0, 0);
;       }
; template <int MODE, int EPI, int BN>
; DI void gemm_phase(CP p, const GArgs& g, int NT, char* smem) {
;     ...
;   for (int e = j; e < total; e += nj) {
;     const int grp = e / (8 * NT);
;     const int rem = e - grp * 8 * NT;
;     const int e2 = e + nj;
;     const bool has_next = can_chain && e2 < total;
;     const int grp2 = e2 / (8 * NT), rem2 = e2 - grp2 * 8 * NT;
;     const int chain = can_chain ? ((first ? 0 : 1) | (has_next ? 2 : 0)) : 0;
;     gemm_tile<MODE, EPI, BN>(p, g, x + 8 * (grp * 8 + (rem & 7)), rem >> 3, smem, chain, x + 8 * (grp2 * 8 + (rem2 & 7)), rem2 >> 3);
.Lgemm_exit_798:
	v_readlane_b32 s60, v255, 0
	v_readlane_b32 s61, v255, 1
	v_readlane_b32 s62, v255, 2
	v_readlane_b32 s63, v255, 3
	v_readlane_b32 s64, v255, 4
	s_setprio 0
	v_mfma_f32_32x32x16_bf16 v[114:129], v[224:227], v[232:235], v[114:129]
	v_mfma_f32_32x32x16_bf16 v[98:113], v[228:231], v[232:235], v[98:113]
	v_mfma_f32_32x32x16_bf16 v[82:97], v[224:227], v[240:243], v[82:97]
	v_mfma_f32_32x32x16_bf16 v[66:81], v[228:231], v[240:243], v[66:81]
	v_mfma_f32_32x32x16_bf16 v[50:65], v[224:227], v[244:247], v[50:65]
	v_mfma_f32_32x32x16_bf16 v[34:49], v[228:231], v[244:247], v[34:49]
	v_mfma_f32_32x32x16_bf16 v[18:33], v[224:227], v[248:251], v[18:33]
	v_mfma_f32_32x32x16_bf16 v[2:17], v[228:231], v[248:251], v[2:17]
	s_add_i32 s95, s95, s76
	s_cmpk_gt_u32 s95, 0x9f
	s_cselect_b64 s[92:93], -1, 0
	s_and_b64 vcc, exec, s[92:93]
	s_cbranch_vccnz .LBB0_801
	s_mul_hi_u32 s2, s95, 0xcccccccd
	s_lshr_b32 s3, s2, 6
	s_mulk_i32 s3, 0xffb0
	s_lshl_b32 s11, s95, 3
	s_add_i32 s3, s3, s95
	s_and_b32 s2, s2, 0xffffc0
	s_and_b32 s11, s11, 56
	s_or_b32 s2, s2, s11
	v_readlane_b32 s11, v252, 38
	s_lshl_b32 s3, s3, 5
	s_or_b32 s2, s2, s11
	s_and_b32 s3, s3, 0xffffff00
	s_lshl_b32 s2, s2, 8
	v_add_u32_e32 v148, s3, v161
	v_add_u32_e32 v138, s2, v157
	v_ashrrev_i32_e32 v149, 31, v148
	v_ashrrev_i32_e32 v139, 31, v138
	v_lshl_add_u64 v[176:177], s[68:69], 0, v[136:137]
	v_lshl_add_u64 v[136:137], s[70:71], 0, v[136:137]
	v_lshlrev_b64 v[148:149], 11, v[148:149]
	v_add3_u32 v0, 0, v168, v169
	v_add_u32_e32 v140, s2, v161
	v_add_u32_e32 v142, s2, v165
	v_add_u32_e32 v144, s2, v167
	v_lshlrev_b64 v[138:139], 11, v[138:139]
	v_lshl_add_u64 v[136:137], v[136:137], 0, v[148:149]
	v_lshl_add_u64 v[148:149], s[70:71], 0, v[134:135]
	v_lshl_add_u64 v[134:135], s[68:69], 0, v[134:135]
	v_readfirstlane_b32 s2, v0
	v_lshl_add_u64 v[134:135], v[134:135], 0, v[138:139]
	s_mov_b32 m0, s2
	v_ashrrev_i32_e32 v141, 31, v140
	global_load_lds_dwordx4 v[134:135], off
	v_add3_u32 v134, 0, v160, v169
	v_ashrrev_i32_e32 v143, 31, v142
	v_lshlrev_b64 v[140:141], 11, v[140:141]
	v_readfirstlane_b32 s2, v134
	v_add3_u32 v135, 0, v162, v169
	v_lshlrev_b64 v[142:143], 11, v[142:143]
	v_lshl_add_u64 v[202:203], s[70:71], 0, v[132:133]
	v_lshl_add_u64 v[132:133], s[68:69], 0, v[132:133]
	v_lshl_add_u64 v[140:141], v[176:177], 0, v[140:141]
	s_mov_b32 m0, s2
	v_readfirstlane_b32 s2, v135
	v_lshl_add_u64 v[132:133], v[132:133], 0, v[142:143]
	global_load_lds_dwordx4 v[140:141], off
	s_mov_b32 m0, s2
	v_ashrrev_i32_e32 v145, 31, v144
	v_add_u32_e32 v146, s3, v157
	global_load_lds_dwordx4 v[132:133], off
	v_add3_u32 v132, 0, v166, v169
	v_ashrrev_i32_e32 v147, 31, v146
	v_lshl_add_u64 v[200:201], s[68:69], 0, v[130:131]
	v_lshlrev_b64 v[144:145], 11, v[144:145]
	v_readfirstlane_b32 s2, v132
	v_add_u32_e32 v0, 0x8000, v0
	v_add_u32_e32 v150, s3, v165
	v_add_u32_e32 v152, s3, v167
	v_lshlrev_b64 v[146:147], 11, v[146:147]
	v_lshl_add_u64 v[144:145], v[200:201], 0, v[144:145]
	s_mov_b32 m0, s2
	v_readfirstlane_b32 s2, v0
	v_add_u32_e32 v0, 0x8000, v134
	v_ashrrev_i32_e32 v151, 31, v150
	v_ashrrev_i32_e32 v153, 31, v152
	v_lshl_add_u64 v[146:147], v[148:149], 0, v[146:147]
	global_load_lds_dwordx4 v[144:145], off
	s_mov_b32 m0, s2
	v_readfirstlane_b32 s2, v0
	v_add_u32_e32 v0, 0x8000, v135
	v_lshlrev_b64 v[150:151], 11, v[150:151]
	v_lshlrev_b64 v[152:153], 11, v[152:153]
	global_load_lds_dwordx4 v[146:147], off
	s_mov_b32 m0, s2
	v_readfirstlane_b32 s2, v0
	v_add_u32_e32 v0, 0x8000, v132
	v_lshl_add_u64 v[152:153], s[70:71], 0, v[152:153]
	v_lshl_add_u64 v[150:151], v[202:203], 0, v[150:151]
	global_load_lds_dwordx4 v[136:137], off
	s_mov_b32 m0, s2
	v_readfirstlane_b32 s2, v0
	global_load_lds_dwordx4 v[150:151], off
	v_lshl_add_u64 v[130:131], v[152:153], 0, v[130:131]
	s_mov_b32 m0, s2
	s_nop 0
	global_load_lds_dwordx4 v[130:131], off

; #define MFMA(a, b, c) __builtin_amdgcn_mfma_f32_32x32x16_bf16((a), (b), (c), 0, 0, 0)
;     ...
;     auto issue_at = [&](int mm0, int nn0, int kt, int buf) {
;       char* lb = L0 + buf * BUFB;
; #pragma unroll
;       for (int i = 0; i < 4; ++i) {
;         const int seg = wv * 4 + i, row = seg * 8 + gl_row;
;         const int c = (lane & 7) ^ ((row >> 1) & 7);
;         const u16* ap = (kt < g.split) ? g.a0 + (size_t)(mm0 + row) * g.ld0 + kt * g.ks0 : g.a1 + (size_t)(mm0 + row) * g.ld1 + (kt - g.split) * 64;
;         __builtin_amdgcn_global_load_lds((const unsigned*)(ap + c * 8), (__attribute__((address_space(3))) unsigned*)(lb + seg * 1024 + lane * 16), 16, 0, 0);
;       }
; #pragma unroll
;       for (int i = 0; i < BN / 64; ++i) {
;         const int seg = wv * (BN / 64) + i, row = seg * 8 + gl_row;
;         const int c = (lane & 7) ^ ((row >> 1) & 7);
;         __builtin_amdgcn_global_load_lds((const unsigned*)(g.W + (size_t)(nn0 + row) * g.K + kt * 64 + c * 8),
;                                          (__attribute__((address_space(3))) unsigned*)(lb + 256 * 128 + seg * 1024 + lane * 16), 16, 0, 0);
;       }
;     };
;     auto issue = [&](int kt, int buf) { issue_at(m0, n0, kt, buf); };
;     auto compute2 = [&](int buf) {
;       const char* lb = L0 + buf * BUFB;
; #pragma unroll
;       for (int ks = 0; ks < 4; ++ks) {
;         const int c = ks * 2 + hh;
;         bf16x8 wf[2], xf[MI];
; #pragma unroll
;         for (int j = 0; j < 2; ++j) { const int r = wn * 64 + j * 32 + l32; wf[j] = *(const bf16x8*)(lb + 256 * 128 + r * 128 + ((c ^ ((r >> 1) & 7)) << 4)); }
; #pragma unroll
;         for (int i = 0; i < MI; ++i) { const int r = wm * (MI * 32) + i * 32 + l32; xf[i] = *(const bf16x8*)(lb + r * 128 + ((c ^ ((r >> 1) & 7)) << 4)); }
; #pragma unroll
;         for (int i = 0; i < MI; ++i) {
;           acc[i][0] = MFMA(wf[0], xf[i], acc[i][0]);
;           acc[i][1] = MFMA(wf[1], xf[i], acc[i][1]);
;         }
;       }
.LBB0_1274:
	v_writelane_b32 v255, s62, 0
	v_writelane_b32 v255, s63, 1
	v_writelane_b32 v255, s64, 2
	v_writelane_b32 v255, s65, 3
	v_writelane_b32 v255, s66, 4
	v_add_u32_e32 v228, v177, v178
	v_add_u32_e32 v229, v169, v178
	v_add_u32_e32 v230, v170, v178
	v_add_u32_e32 v231, v172, v178
	s_nop 0
	v_readfirstlane_b32 s62, v228
	v_readfirstlane_b32 s63, v229
	v_readfirstlane_b32 s64, v230
	v_readfirstlane_b32 s65, v231
	v_readfirstlane_b32 s98, v179
	s_nop 3
	s_lshr_b32 s98, s98, 6
	s_cmp_ge_u32 s98, 4
	s_cbranch_scc0 .Lgemm_prio_1274
	s_setprio 1
.Lgemm_prio_1274:
	s_and_b32 s59, s56, 0x10000
	s_xor_b32 s60, s59, 0x10000
	s_add_i32 s57, s58, 1
	s_add_i32 s60, s60, 0
	s_cmp_lt_u32 s58, 21
	s_cselect_b64 vcc, -1, 0
	v_add_u32_e32 v233, s59, v201
	v_add_u32_e32 v230, v233, v175
	v_add_u32_e32 v234, v233, v174
	ds_read_b128 v[202:205], v230 offset:32768
	ds_read_b128 v[206:209], v230 offset:36864
	ds_read_b128 v[210:213], v234
	ds_read_b128 v[214:217], v234 offset:4096
	ds_read_b128 v[218:221], v234 offset:8192
	ds_read_b128 v[222:225], v234 offset:12288
	s_add_i32 s66, s60, 0x8000
	v_lshl_add_u64 v[226:227], v[160:161], 0, s[2:3]
	v_lshl_add_u64 v[228:229], v[144:145], 0, s[2:3]
	v_cndmask_b32_e32 v227, v229, v227, vcc
	v_cndmask_b32_e32 v226, v228, v226, vcc
	v_lshl_add_u64 v[226:227], v[0:1], 1, v[226:227]
	s_add_i32 m0, s60, s62
	v_lshl_add_u64 v[228:229], v[142:143], 0, s[2:3]
	global_load_lds_dwordx4 v[226:227], off
	v_lshl_add_u64 v[226:227], v[158:159], 0, s[2:3]
	v_cndmask_b32_e32 v227, v229, v227, vcc
	v_cndmask_b32_e32 v226, v228, v226, vcc
	v_lshl_add_u64 v[226:227], v[130:131], 1, v[226:227]
	s_add_i32 m0, s60, s63
	v_lshl_add_u64 v[228:229], v[140:141], 0, s[2:3]
	global_load_lds_dwordx4 v[226:227], off
	v_lshl_add_u64 v[226:227], v[156:157], 0, s[2:3]
	v_cndmask_b32_e32 v227, v229, v227, vcc
	v_cndmask_b32_e32 v226, v228, v226, vcc
	v_lshl_add_u64 v[226:227], v[132:133], 1, v[226:227]
	s_add_i32 m0, s60, s64
	v_lshl_add_u64 v[228:229], v[138:139], 0, s[2:3]
	global_load_lds_dwordx4 v[226:227], off
	v_lshl_add_u64 v[226:227], v[154:155], 0, s[2:3]
	v_cndmask_b32_e32 v226, v228, v226, vcc
	v_cndmask_b32_e32 v227, v229, v227, vcc
	s_add_i32 m0, s60, s65
	v_lshl_add_u64 v[226:227], v[134:135], 1, v[226:227]
	global_load_lds_dwordx4 v[226:227], off
	s_add_i32 m0, s66, s62
	v_lshl_add_u64 v[226:227], v[146:147], 0, s[2:3]
	global_load_lds_dwordx4 v[226:227], off
	s_add_i32 m0, s66, s63
	v_lshl_add_u64 v[226:227], v[148:149], 0, s[2:3]
	global_load_lds_dwordx4 v[226:227], off
	s_add_i32 m0, s66, s64
	v_lshl_add_u64 v[226:227], v[150:151], 0, s[2:3]
	global_load_lds_dwordx4 v[226:227], off
	v_lshl_add_u64 v[226:227], v[152:153], 0, s[2:3]
	s_add_i32 m0, s66, s65
	s_add_i32 s58, s59, 0
	global_load_lds_dwordx4 v[226:227], off
	v_add_u32_e32 v233, s59, v200
	v_add_u32_e32 v230, v233, v175
	v_add_u32_e32 v234, v233, v174
	s_waitcnt lgkmcnt(3)
	v_mfma_f32_32x32x16_bf16 v[114:129], v[202:205], v[210:213], 0
	s_add_u32 s2, s2, 0x80
	s_addc_u32 s3, s3, 0
	s_add_i32 s56, s56, 0x10000
	s_cmpk_eq_i32 s2, 0x1580
	s_mov_b32 s58, s57
	ds_read_b128 v[240:243], v230 offset:32768
	v_mfma_f32_32x32x16_bf16 v[98:113], v[206:209], v[210:213], 0
	ds_read_b128 v[244:247], v230 offset:36864
	s_waitcnt lgkmcnt(4)
	v_mfma_f32_32x32x16_bf16 v[82:97], v[202:205], v[214:217], 0
	ds_read_b128 v[248:251], v234
	v_mfma_f32_32x32x16_bf16 v[66:81], v[206:209], v[214:217], 0
	ds_read_b128 v[214:217], v234 offset:4096
	s_waitcnt lgkmcnt(5)
	v_mfma_f32_32x32x16_bf16 v[50:65], v[202:205], v[218:221], 0
	v_mfma_f32_32x32x16_bf16 v[34:49], v[206:209], v[218:221], 0
	ds_read_b128 v[218:221], v234 offset:8192
	s_waitcnt lgkmcnt(5)
	v_mfma_f32_32x32x16_bf16 v[18:33], v[202:205], v[222:225], 0
	v_mfma_f32_32x32x16_bf16 v[2:17], v[206:209], v[222:225], 0
	ds_read_b128 v[222:225], v234 offset:12288
	s_branch .Lgemm_g1_1274

;     ...
;     auto issue_at = [&](int mm0, int nn0, int kt, int buf) {
;       char* lb = L0 + buf * BUFB;
; #pragma unroll
;       for (int i = 0; i < 4; ++i) {
;         const int seg = wv * 4 + i, row = seg * 8 + gl_row;
;         const int c = (lane & 7) ^ ((row >> 1) & 7);
;         const u16* ap = (kt < g.split) ? g.a0 + (size_t)(mm0 + row) * g.ld0 + kt * g.ks0 : g.a1 + (size_t)(mm0 + row) * g.ld1 + (kt - g.split) * 64;
;         __builtin_amdgcn_global_load_lds((const unsigned*)(ap + c * 8), (__attribute__((address_space(3))) unsigned*)(lb + seg * 1024 + lane * 16), 16, 0, 0);
;       }
; #pragma unroll
;       for (int i = 0; i < BN / 64; ++i) {
;         const int seg = wv * (BN / 64) + i, row = seg * 8 + gl_row;
;         const int c = (lane & 7) ^ ((row >> 1) & 7);
;         __builtin_amdgcn_global_load_lds((const unsigned*)(g.W + (size_t)(nn0 + row) * g.K + kt * 64 + c * 8),
;                                          (__attribute__((address_space(3))) unsigned*)(lb + 256 * 128 + seg * 1024 + lane * 16), 16, 0, 0);
;       }
; template <int MODE, int EPI, int BN>
; DI void gemm_phase(CP p, const GArgs& g, int NT, char* smem) {
;     ...
;   for (int e = j; e < total; e += nj) {
;     const int grp = e / (8 * NT);
;     const int rem = e - grp * 8 * NT;
;     const int e2 = e + nj;
;     const bool has_next = can_chain && e2 < total;
;     const int grp2 = e2 / (8 * NT), rem2 = e2 - grp2 * 8 * NT;
;     const int chain = can_chain ? ((first ? 0 : 1) | (has_next ? 2 : 0)) : 0;
;     gemm_tile<MODE, EPI, BN>(p, g, x + 8 * (grp * 8 + (rem & 7)), rem >> 3, smem, chain, x + 8 * (grp2 * 8 + (rem2 & 7)), rem2 >> 3);
.Lgemm_exit_1274:
	v_readlane_b32 s62, v255, 0
	v_readlane_b32 s63, v255, 1
	v_readlane_b32 s64, v255, 2
	v_readlane_b32 s65, v255, 3
	v_readlane_b32 s66, v255, 4
	s_setprio 0
	v_mfma_f32_32x32x16_bf16 v[114:129], v[240:243], v[248:251], v[114:129]
	v_mfma_f32_32x32x16_bf16 v[98:113], v[244:247], v[248:251], v[98:113]
	v_mfma_f32_32x32x16_bf16 v[82:97], v[240:243], v[214:217], v[82:97]
	v_mfma_f32_32x32x16_bf16 v[66:81], v[244:247], v[214:217], v[66:81]
	v_mfma_f32_32x32x16_bf16 v[50:65], v[240:243], v[218:221], v[50:65]
	v_mfma_f32_32x32x16_bf16 v[34:49], v[244:247], v[218:221], v[34:49]
	v_mfma_f32_32x32x16_bf16 v[18:33], v[240:243], v[222:225], v[18:33]
	v_mfma_f32_32x32x16_bf16 v[2:17], v[244:247], v[222:225], v[2:17]
	s_add_i32 s15, s15, s10
	s_cmp_gt_u32 s15, 63
	s_cselect_b64 s[58:59], -1, 0
	s_and_b64 vcc, exec, s[58:59]
	s_cbranch_vccnz .LBB0_1277
	s_lshr_b32 s2, s15, 2
	s_and_b32 s2, s2, 0xffffff8
	s_and_b32 s3, s15, 7
	s_or_b32 s3, s2, s3
	s_lshl_b32 s2, s2, 7
	s_lshl_b32 s56, s15, 5
	s_sub_i32 s2, s56, s2
	s_lshl_b32 s3, s3, 11
	s_and_b32 s2, s2, 0xffffff00
	s_or_b32 s3, s3, s71
	v_add_u32_e32 v144, s2, v173
	v_lshlrev_b64 v[130:131], 1, v[130:131]
	v_mov_b64_e32 v[142:143], s[46:47]
	v_lshlrev_b64 v[132:133], 1, v[132:133]
	v_add_u32_e32 v0, s3, v163
	v_add_u32_e32 v148, s3, v168
	v_add_u32_e32 v149, s3, v171
	v_add_u32_e32 v150, s3, v173
	v_add_u32_e32 v151, s2, v163
	v_add_u32_e32 v146, s2, v168
	v_add_u32_e32 v147, s2, v171
	v_lshl_add_u64 v[138:139], s[42:43], 0, v[130:131]
	v_lshlrev_b64 v[134:135], 1, v[134:135]
	v_lshl_add_u64 v[130:131], s[46:47], 0, v[130:131]
	v_mad_i64_i32 v[142:143], s[2:3], v144, s96, v[142:143]
	v_lshl_add_u64 v[144:145], s[46:47], 0, v[132:133]
	v_lshl_add_u64 v[140:141], s[42:43], 0, v[134:135]
	v_mad_i64_i32 v[144:145], s[2:3], v147, s96, v[144:145]
	v_mad_i64_i32 v[130:131], s[2:3], v146, s96, v[130:131]
	v_lshl_add_u64 v[146:147], s[46:47], 0, v[136:137]
	v_lshl_add_u64 v[132:133], s[42:43], 0, v[132:133]
	v_lshl_add_u64 v[136:137], s[42:43], 0, v[136:137]
	v_mad_i64_i32 v[146:147], s[2:3], v151, s96, v[146:147]
	v_mad_i64_i32 v[140:141], s[2:3], v150, s29, v[140:141]
	v_mad_i64_i32 v[132:133], s[2:3], v149, s29, v[132:133]
	v_mad_i64_i32 v[138:139], s[2:3], v148, s29, v[138:139]
	v_mad_i64_i32 v[136:137], s[2:3], v0, s29, v[136:137]
	v_add3_u32 v0, 0, v177, v178
	s_nop 0
	v_readfirstlane_b32 s2, v0
	s_mov_b32 m0, s2
	v_add_u32_e32 v0, 0x8000, v0
	global_load_lds_dwordx4 v[136:137], off
	v_add3_u32 v136, 0, v169, v178
	v_add3_u32 v137, 0, v170, v178
	v_readfirstlane_b32 s2, v136
	s_mov_b32 m0, s2
	v_readfirstlane_b32 s2, v137
	global_load_lds_dwordx4 v[138:139], off
	s_mov_b32 m0, s2
	s_nop 0
	global_load_lds_dwordx4 v[132:133], off
	v_add3_u32 v132, 0, v172, v178
	s_nop 0
	v_readfirstlane_b32 s2, v132
	s_mov_b32 m0, s2
	v_readfirstlane_b32 s2, v0
	v_add_u32_e32 v0, 0x8000, v136
	global_load_lds_dwordx4 v[140:141], off
	s_mov_b32 m0, s2
	v_readfirstlane_b32 s2, v0
	v_add_u32_e32 v0, 0x8000, v137
	global_load_lds_dwordx4 v[146:147], off
	s_mov_b32 m0, s2
	v_readfirstlane_b32 s2, v0
	v_add_u32_e32 v0, 0x8000, v132
	global_load_lds_dwordx4 v[130:131], off
	s_mov_b32 m0, s2
	v_readfirstlane_b32 s2, v0
	global_load_lds_dwordx4 v[144:145], off
	v_lshl_add_u64 v[130:131], v[142:143], 0, v[134:135]
	s_mov_b32 m0, s2
	s_nop 0
	global_load_lds_dwordx4 v[130:131], off

; #define MFMA(a, b, c) __builtin_amdgcn_mfma_f32_32x32x16_bf16((a), (b), (c), 0, 0, 0)
;     ...
;     auto issue_at = [&](int mm0, int nn0, int kt, int buf) {
;       char* lb = L0 + buf * BUFB;
; #pragma unroll
;       for (int i = 0; i < 4; ++i) {
;         const int seg = wv * 4 + i, row = seg * 8 + gl_row;
;         const int c = (lane & 7) ^ ((row >> 1) & 7);
;         const u16* ap = (kt < g.split) ? g.a0 + (size_t)(mm0 + row) * g.ld0 + kt * g.ks0 : g.a1 + (size_t)(mm0 + row) * g.ld1 + (kt - g.split) * 64;
;         __builtin_amdgcn_global_load_lds((const unsigned*)(ap + c * 8), (__attribute__((address_space(3))) unsigned*)(lb + seg * 1024 + lane * 16), 16, 0, 0);
;       }
; #pragma unroll
;       for (int i = 0; i < BN / 64; ++i) {
;         const int seg = wv * (BN / 64) + i, row = seg * 8 + gl_row;
;         const int c = (lane & 7) ^ ((row >> 1) & 7);
;         __builtin_amdgcn_global_load_lds((const unsigned*)(g.W + (size_t)(nn0 + row) * g.K + kt * 64 + c * 8),
;                                          (__attribute__((address_space(3))) unsigned*)(lb + 256 * 128 + seg * 1024 + lane * 16), 16, 0, 0);
;       }
;     };
;     auto issue = [&](int kt, int buf) { issue_at(m0, n0, kt, buf); };
;     auto compute2 = [&](int buf) {
;       const char* lb = L0 + buf * BUFB;
; #pragma unroll
;       for (int ks = 0; ks < 4; ++ks) {
;         const int c = ks * 2 + hh;
;         bf16x8 wf[2], xf[MI];
; #pragma unroll
;         for (int j = 0; j < 2; ++j) { const int r = wn * 64 + j * 32 + l32; wf[j] = *(const bf16x8*)(lb + 256 * 128 + r * 128 + ((c ^ ((r >> 1) & 7)) << 4)); }
; #pragma unroll
;         for (int i = 0; i < MI; ++i) { const int r = wm * (MI * 32) + i * 32 + l32; xf[i] = *(const bf16x8*)(lb + r * 128 + ((c ^ ((r >> 1) & 7)) << 4)); }
; #pragma unroll
;         for (int i = 0; i < MI; ++i) {
;           acc[i][0] = MFMA(wf[0], xf[i], acc[i][0]);
;           acc[i][1] = MFMA(wf[1], xf[i], acc[i][1]);
;         }
;       }
.LBB0_1371:
	s_waitcnt vmcnt(16)
	s_barrier
	v_writelane_b32 v255, s60, 0
	v_writelane_b32 v255, s61, 1
	v_writelane_b32 v255, s62, 2
	v_writelane_b32 v255, s63, 3
	v_writelane_b32 v255, s64, 4
	v_add_u32_e32 v0, v167, v168
	v_add_u32_e32 v175, v157, v168
	v_add_u32_e32 v178, v159, v168
	v_add_u32_e32 v199, v165, v168
	s_nop 0
	v_readfirstlane_b32 s60, v0
	v_readfirstlane_b32 s61, v175
	v_readfirstlane_b32 s62, v178
	v_readfirstlane_b32 s63, v199
	v_readfirstlane_b32 s98, v179
	s_nop 3
	s_lshr_b32 s98, s98, 6
	s_cmp_ge_u32 s98, 4
	s_cbranch_scc0 .Lgemm_prio_1371
	s_setprio 1
.Lgemm_prio_1371:
	s_and_b32 s17, s16, 0x10000
	s_xor_b32 s43, s17, 0x10000
	s_add_i32 s43, s43, 0
	s_add_i32 s17, s17, 0
	v_add_u32_e32 v0, s17, v174
	v_add_u32_e32 v175, v0, v170
	v_add_u32_e32 v0, v0, v169
	ds_read_b128 v[200:203], v175 offset:32768
	ds_read_b128 v[204:207], v175 offset:36864
	ds_read_b128 v[208:211], v0
	ds_read_b128 v[212:215], v0 offset:4096
	ds_read_b128 v[216:219], v0 offset:8192
	ds_read_b128 v[220:223], v0 offset:12288
	s_add_i32 s64, s43, 0x8000
	s_add_i32 m0, s43, s60
	v_lshl_add_u64 v[176:177], v[152:153], 0, s[10:11]
	global_load_lds_dwordx4 v[176:177], off
	s_add_i32 m0, s43, s61
	v_lshl_add_u64 v[176:177], v[150:151], 0, s[10:11]
	global_load_lds_dwordx4 v[176:177], off
	s_add_i32 m0, s43, s62
	v_lshl_add_u64 v[176:177], v[148:149], 0, s[10:11]
	global_load_lds_dwordx4 v[176:177], off
	s_add_i32 m0, s43, s63
	v_lshl_add_u64 v[176:177], v[146:147], 0, s[10:11]
	global_load_lds_dwordx4 v[176:177], off
	s_add_i32 m0, s64, s60
	v_lshl_add_u64 v[176:177], v[144:145], 0, s[10:11]
	global_load_lds_dwordx4 v[176:177], off
	s_add_i32 m0, s64, s61
	v_lshl_add_u64 v[176:177], v[142:143], 0, s[10:11]
	global_load_lds_dwordx4 v[176:177], off
	s_add_i32 m0, s64, s62
	v_lshl_add_u64 v[176:177], v[140:141], 0, s[10:11]
	global_load_lds_dwordx4 v[176:177], off
	s_add_i32 m0, s64, s63
	v_lshl_add_u64 v[176:177], v[138:139], 0, s[10:11]
	global_load_lds_dwordx4 v[176:177], off
	v_add_u32_e32 v0, s17, v173
	v_add_u32_e32 v175, v0, v170
	v_add_u32_e32 v0, v0, v169
	s_waitcnt lgkmcnt(3)
	v_mfma_f32_32x32x16_bf16 v[114:129], v[200:203], v[208:211], 0
	s_add_i32 s16, s16, 0x10000
	s_add_u32 s10, s10, 0x80
	s_addc_u32 s11, s11, 0
	s_cmpk_eq_i32 s10, 0x780
	ds_read_b128 v[224:227], v175 offset:32768
	v_mfma_f32_32x32x16_bf16 v[98:113], v[204:207], v[208:211], 0
	ds_read_b128 v[228:231], v175 offset:36864
	s_waitcnt lgkmcnt(4)
	v_mfma_f32_32x32x16_bf16 v[82:97], v[200:203], v[212:215], 0
	ds_read_b128 v[232:235], v0
	v_mfma_f32_32x32x16_bf16 v[66:81], v[204:207], v[212:215], 0
	ds_read_b128 v[240:243], v0 offset:4096
	s_waitcnt lgkmcnt(5)
	v_mfma_f32_32x32x16_bf16 v[50:65], v[200:203], v[216:219], 0
	ds_read_b128 v[244:247], v0 offset:8192
	v_mfma_f32_32x32x16_bf16 v[34:49], v[204:207], v[216:219], 0
	ds_read_b128 v[248:251], v0 offset:12288
	s_waitcnt lgkmcnt(6)
	v_mfma_f32_32x32x16_bf16 v[18:33], v[200:203], v[220:223], 0
	v_mfma_f32_32x32x16_bf16 v[2:17], v[204:207], v[220:223], 0
	s_branch .Lgemm_g1_1371

;     ...
;     auto issue_at = [&](int mm0, int nn0, int kt, int buf) {
;       char* lb = L0 + buf * BUFB;
; #pragma unroll
;       for (int i = 0; i < 4; ++i) {
;         const int seg = wv * 4 + i, row = seg * 8 + gl_row;
;         const int c = (lane & 7) ^ ((row >> 1) & 7);
;         const u16* ap = (kt < g.split) ? g.a0 + (size_t)(mm0 + row) * g.ld0 + kt * g.ks0 : g.a1 + (size_t)(mm0 + row) * g.ld1 + (kt - g.split) * 64;
;         __builtin_amdgcn_global_load_lds((const unsigned*)(ap + c * 8), (__attribute__((address_space(3))) unsigned*)(lb + seg * 1024 + lane * 16), 16, 0, 0);
;       }
; #pragma unroll
;       for (int i = 0; i < BN / 64; ++i) {
;         const int seg = wv * (BN / 64) + i, row = seg * 8 + gl_row;
;         const int c = (lane & 7) ^ ((row >> 1) & 7);
;         __builtin_amdgcn_global_load_lds((const unsigned*)(g.W + (size_t)(nn0 + row) * g.K + kt * 64 + c * 8),
;                                          (__attribute__((address_space(3))) unsigned*)(lb + 256 * 128 + seg * 1024 + lane * 16), 16, 0, 0);
;       }
; template <int MODE, int EPI, int BN>
; DI void gemm_phase(CP p, const GArgs& g, int NT, char* smem) {
;     ...
;   for (int e = j; e < total; e += nj) {
;     const int grp = e / (8 * NT);
;     const int rem = e - grp * 8 * NT;
;     const int e2 = e + nj;
;     const bool has_next = can_chain && e2 < total;
;     const int grp2 = e2 / (8 * NT), rem2 = e2 - grp2 * 8 * NT;
;     const int chain = can_chain ? ((first ? 0 : 1) | (has_next ? 2 : 0)) : 0;
;     gemm_tile<MODE, EPI, BN>(p, g, x + 8 * (grp * 8 + (rem & 7)), rem >> 3, smem, chain, x + 8 * (grp2 * 8 + (rem2 & 7)), rem2 >> 3);
.Lgemm_exit_1371:
	v_readlane_b32 s60, v255, 0
	v_readlane_b32 s61, v255, 1
	v_readlane_b32 s62, v255, 2
	v_readlane_b32 s63, v255, 3
	v_readlane_b32 s64, v255, 4
	s_setprio 0
	v_mfma_f32_32x32x16_bf16 v[114:129], v[224:227], v[232:235], v[114:129]
	v_mfma_f32_32x32x16_bf16 v[98:113], v[228:231], v[232:235], v[98:113]
	v_mfma_f32_32x32x16_bf16 v[82:97], v[224:227], v[240:243], v[82:97]
	v_mfma_f32_32x32x16_bf16 v[66:81], v[228:231], v[240:243], v[66:81]
	v_mfma_f32_32x32x16_bf16 v[50:65], v[224:227], v[244:247], v[50:65]
	v_mfma_f32_32x32x16_bf16 v[34:49], v[228:231], v[244:247], v[34:49]
	v_mfma_f32_32x32x16_bf16 v[18:33], v[224:227], v[248:251], v[18:33]
	v_mfma_f32_32x32x16_bf16 v[2:17], v[228:231], v[248:251], v[2:17]
	s_add_i32 s51, s51, s50
	s_cmpk_gt_u32 s51, 0x15f
	s_cselect_b64 s[10:11], -1, 0
	s_and_b64 vcc, exec, s[10:11]
	s_cbranch_vccnz .LBB0_1374
	s_mul_hi_u32 s16, s51, 0xba2e8ba3
	s_lshr_b32 s16, s16, 7
	s_mul_i32 s17, s16, 0xffffff50
	s_lshl_b32 s43, s51, 3
	s_add_i32 s17, s17, s51
	s_lshl_b32 s16, s16, 6
	s_and_b32 s43, s43, 56
	s_or_b32 s16, s16, s43
	s_lshl_b32 s17, s17, 5
	s_or_b32 s16, s16, s72
	s_and_b32 s17, s17, 0xffffff00
	s_lshl_b32 s16, s16, 8
	v_add_u32_e32 v148, s17, v158
	v_add_u32_e32 v138, s16, v156
	v_ashrrev_i32_e32 v149, 31, v148
	v_ashrrev_i32_e32 v139, 31, v138
	v_lshl_add_u64 v[176:177], s[46:47], 0, v[136:137]
	v_lshl_add_u64 v[136:137], s[48:49], 0, v[136:137]
	v_lshlrev_b64 v[148:149], 11, v[148:149]
	v_add3_u32 v0, 0, v167, v168
	v_add_u32_e32 v140, s16, v158
	v_add_u32_e32 v142, s16, v164
	v_add_u32_e32 v144, s16, v166
	v_lshlrev_b64 v[138:139], 11, v[138:139]
	v_lshl_add_u64 v[136:137], v[136:137], 0, v[148:149]
	v_lshl_add_u64 v[148:149], s[48:49], 0, v[134:135]
	v_lshl_add_u64 v[134:135], s[46:47], 0, v[134:135]
	v_readfirstlane_b32 s16, v0
	v_lshl_add_u64 v[134:135], v[134:135], 0, v[138:139]
	s_mov_b32 m0, s16
	v_ashrrev_i32_e32 v141, 31, v140
	global_load_lds_dwordx4 v[134:135], off
	v_add3_u32 v134, 0, v157, v168
	v_ashrrev_i32_e32 v143, 31, v142
	v_lshlrev_b64 v[140:141], 11, v[140:141]
	v_readfirstlane_b32 s16, v134
	v_add3_u32 v135, 0, v159, v168
	v_lshlrev_b64 v[142:143], 11, v[142:143]
	v_lshl_add_u64 v[202:203], s[48:49], 0, v[132:133]
	v_lshl_add_u64 v[132:133], s[46:47], 0, v[132:133]
	v_lshl_add_u64 v[140:141], v[176:177], 0, v[140:141]
	s_mov_b32 m0, s16
	v_readfirstlane_b32 s16, v135
	v_lshl_add_u64 v[132:133], v[132:133], 0, v[142:143]
	global_load_lds_dwordx4 v[140:141], off
	s_mov_b32 m0, s16
	v_ashrrev_i32_e32 v145, 31, v144
	v_add_u32_e32 v146, s17, v156
	global_load_lds_dwordx4 v[132:133], off
	v_add3_u32 v132, 0, v165, v168
	v_ashrrev_i32_e32 v147, 31, v146
	v_lshl_add_u64 v[200:201], s[46:47], 0, v[130:131]
	v_lshlrev_b64 v[144:145], 11, v[144:145]
	v_readfirstlane_b32 s16, v132
	v_add_u32_e32 v0, 0x8000, v0
	v_add_u32_e32 v150, s17, v164
	v_add_u32_e32 v152, s17, v166
	v_lshlrev_b64 v[146:147], 11, v[146:147]
	v_lshl_add_u64 v[144:145], v[200:201], 0, v[144:145]
	s_mov_b32 m0, s16
	v_readfirstlane_b32 s16, v0
	v_add_u32_e32 v0, 0x8000, v134
	v_ashrrev_i32_e32 v151, 31, v150
	v_ashrrev_i32_e32 v153, 31, v152
	v_lshl_add_u64 v[146:147], v[148:149], 0, v[146:147]
	global_load_lds_dwordx4 v[144:145], off
	s_mov_b32 m0, s16
	v_readfirstlane_b32 s16, v0
	v_add_u32_e32 v0, 0x8000, v135
	v_lshlrev_b64 v[150:151], 11, v[150:151]
	v_lshlrev_b64 v[152:153], 11, v[152:153]
	global_load_lds_dwordx4 v[146:147], off
	s_mov_b32 m0, s16
	v_readfirstlane_b32 s16, v0
	v_add_u32_e32 v0, 0x8000, v132
	v_lshl_add_u64 v[152:153], s[48:49], 0, v[152:153]
	v_lshl_add_u64 v[150:151], v[202:203], 0, v[150:151]
	global_load_lds_dwordx4 v[136:137], off
	s_mov_b32 m0, s16
	v_readfirstlane_b32 s16, v0
	global_load_lds_dwordx4 v[150:151], off
	v_lshl_add_u64 v[130:131], v[152:153], 0, v[130:131]
	s_mov_b32 m0, s16
	s_nop 0
	global_load_lds_dwordx4 v[130:131], off
